# code placement: the hand-written attention code (loop heads were at 4 mod 8 bytes) shifted by one 4-byte s_nop, steps region restored by a second one
# baseline (speedup 1.0000x reference)
; DI unsigned xb_ld(unsigned* p)              { return __hip_atomic_load(p, __ATOMIC_RELAXED, __HIP_MEMORY_SCOPE_AGENT); }
; DI void xcd_barrier_complete(unsigned* bar, unsigned x, unsigned& nloc, unsigned& nx) {
;     const unsigned G = gridDim.x * gridDim.y * gridDim.z;
;     unsigned sum, cnt, mine, sp = 0u;
;     for (;;) {
;         sum = 0u; cnt = 0u; mine = 0u;
; #pragma unroll
;         for (unsigned j = 0; j < 16; ++j) { const unsigned c = xb_ld(&bar[XB_XCNT(j)]); sum += c; cnt += (c > 0u) ? 1u : 0u; mine = (j == x) ? c : mine; }
; DI void xcd_barrier(const XcdBarrier& b) {
;     asm volatile("s_waitcnt vmcnt(0)" ::: "memory");
;     __syncthreads();
;     if (threadIdx.x == 0) {
;         unsigned* bar = b.bar;
;         __builtin_amdgcn_s_waitcnt(0);
;         unsigned nloc = b.st[0], nx = b.st[1];
;         if (nloc == 0u) { xcd_barrier_complete(bar, b.x, nloc, nx); b.st[0] = nloc; b.st[1] = nx; }
.LBB0_547:
	s_nop 0
	s_cmp_gt_i32 s39, 2
	s_waitcnt lgkmcnt(0)
	s_cselect_b64 s[0:1], -1, 0
	s_and_b64 s[4:5], s[14:15], s[0:1]
	s_andn2_b64 vcc, exec, s[4:5]
	s_cbranch_vccnz .LBB0_597
	s_waitcnt vmcnt(0)
	v_cmp_eq_u32_e32 vcc, 0, v226
	s_waitcnt vmcnt(0)
	s_barrier
	s_and_saveexec_b64 s[4:5], vcc
	s_cbranch_execz .LBB0_596
	s_add_u32 s6, s36, 0x4200
	s_addc_u32 s7, s37, 0
	s_add_i32 s8, 0, 0x22000
	v_mov_b32_e32 v0, s8
	s_waitcnt vmcnt(0) expcnt(0) lgkmcnt(0)
	ds_read_b32 v2, v0
	s_add_i32 s8, 0, 0x22004
	v_mov_b32_e32 v0, s8
	ds_read_b32 v0, v0
	s_waitcnt lgkmcnt(1)
	v_cmp_ne_u32_e32 vcc, 0, v2
	s_cbranch_vccnz .LBB0_564
	s_add_u32 s8, s36, 0x4400
	s_addc_u32 s9, s37, 0
	s_add_u32 s10, s36, 0x4500
	s_addc_u32 s11, s37, 0
	s_add_u32 s12, s36, 0x4600
	s_addc_u32 s13, s37, 0
	s_add_u32 s14, s36, 0x4700
	s_addc_u32 s15, s37, 0
	s_add_u32 s16, s36, 0x4800
	s_addc_u32 s17, s37, 0
	s_add_u32 s18, s36, 0x4900
	s_addc_u32 s19, s37, 0
	s_add_u32 s20, s36, 0x4a00
	s_addc_u32 s21, s37, 0
	s_add_u32 s22, s36, 0x4b00
	s_addc_u32 s23, s37, 0
	s_add_u32 s24, s36, 0x4c00
	s_addc_u32 s25, s37, 0
	s_add_u32 s26, s36, 0x4d00
	s_addc_u32 s27, s37, 0
	s_add_u32 s28, s36, 0x4e00
	s_addc_u32 s29, s37, 0
	s_add_u32 s30, s36, 0x4f00
	s_addc_u32 s31, s37, 0
	v_readlane_b32 s44, v253, 3
	s_add_u32 s34, s36, 0x5000
	v_readlane_b32 s45, v253, 4
	s_addc_u32 s35, s37, 0
	s_load_dwordx2 s[48:49], s[44:45], 0x4
	s_add_u32 s42, s36, 0x5100
	s_addc_u32 s43, s37, 0
	s_add_u32 s44, s36, 0x5200
	s_addc_u32 s45, s37, 0
	v_readlane_b32 s33, v253, 0
	s_add_u32 s46, s36, 0x5300
	s_waitcnt lgkmcnt(0)
	s_mul_i32 s33, s48, s33
	s_addc_u32 s47, s37, 0
	s_mul_i32 s33, s33, s49
	s_mov_b32 s54, 1
	v_mov_b32_e32 v16, 0
	s_branch .LBB0_552

; __global__ void __launch_bounds__(512, 2) fwd_kernel(Args a_byval) {
;     ...
;         for (int step = 0; step < 6; ++step) {
;             int kind, rs, rstr = 32, rc;
;             if (step == 0) { kind = 3; rs = v; rc = 1; }
;             else if (step == 1) { kind = 3; rs = 256 + 4 * x + j; rc = j < 4 ? 1 : 0; }
;             else if (step == 2) { kind = 4; rs = 88 * x + j; rstr = 28; rc = j < 4 ? 1 : 3; }
;             else if (step == 3) { kind = 5; rs = 4 * x + j; rc = j < 4 ? 1 : 0; }
;             else if (step == 4) { kind = 4; const int base = 704 + (x < 6 ? 113 * x : 678 + 112 * (x - 6)), r = (x < 6 ? 25 : 24);
;                 if (j < 4) { rs = base + j; rc = 1; } else { const int jj = j - 4; rs = base + 4 + jj; rstr = 28; rc = 3 + (jj < r ? 1 : 0); } }
;             else { kind = 5; rs = 32 + v; rc = 1; }
;             if (kind == 3) {
.LBB0_767:
	s_nop 0
	s_cmp_lt_i32 s83, 2
	s_mov_b64 s[4:5], -1
	s_cbranch_scc1 .LBB0_797
	s_cmp_lt_i32 s83, 3
	s_cbranch_scc1 .LBB0_777
	s_cmp_lt_i32 s83, 4
	s_cbranch_scc1 .LBB0_774
	s_cmp_lg_u32 s83, 4
	s_mov_b64 s[0:1], -1
	s_cbranch_scc0 .LBB0_772
	s_mov_b64 s[0:1], 0
